# L5 queue: second fetch needs no ticket (256 static items); L3 finalize: dropped the redundant L1 invalidate after the split-K count wait
# baseline (speedup 1.0000x reference)
; DI float silu(float x) { return x * __builtin_amdgcn_rcpf(1.f + __expf(-x)); }
; __global__ void __launch_bounds__(NTHR) fwd_megakernel(Params p) {
;     ...
;     { PHASE_VARS
;       if (tid == 0) { unsigned sp_ = 0; while (__hip_atomic_load(ctr + l * 4 + 3, __ATOMIC_RELAXED, __HIP_MEMORY_SCOPE_AGENT) < 64u) { __builtin_amdgcn_s_sleep(1); if (++sp_ > (1u << 24)) break; }
;         __builtin_amdgcn_fence(__ATOMIC_ACQUIRE, "agent"); asm volatile("s_waitcnt vmcnt(0)" ::: "memory"); }
;       __syncthreads(); }
;     { PHASE_VARS const float* cpart = (const float*)(ws + O_CPART); bf16_t* kc_ = (bf16_t*)(ws + O_KC); bf16_t* vct = (bf16_t*)(ws + O_VCT);
;       float* hid = (float*)lds; float* red = (float*)lds + 128;
;       for (int row = bid; row < 2048; row += nblk) {
;         const int kv = row >> 10, rr = row & 1023, b = rr >> 9, n = (rr & 511) >> 1, g = rr & 1;
;         __syncthreads();
;         if (tid < 128) { float s = 0; for (int k = 0; k < 8; ++k) s += cpart[((size_t)k * 2048 + row) * 256 + kv * 128 + tid]; hid[tid] = silu(s); }
.LBB0_1083:
	v_readlane_b32 s2, v252, 43
	v_readlane_b32 s3, v252, 44
	s_nop 4
	global_load_dword v0, v1, s[2:3] offset:12 sc1
	s_mov_b64 s[2:3], -1
	s_waitcnt vmcnt(0)
	v_cmp_lt_u32_e32 vcc, 63, v0
	s_cbranch_vccnz .LBB0_1082
	s_cmp_lg_u32 s4, 0
	s_sleep 1
	s_cbranch_scc0 .LBB0_1081
	v_readlane_b32 s2, v252, 43
	v_readlane_b32 s3, v252, 44
	s_nop 4
	global_load_dword v0, v1, s[2:3] offset:12 sc1
	s_mov_b64 s[2:3], -1
	s_waitcnt vmcnt(0)
	v_cmp_gt_u32_e32 vcc, 64, v0
	s_cbranch_vccz .LBB0_1082
	v_readlane_b32 s2, v252, 43
	v_readlane_b32 s3, v252, 44
	s_sleep 1
	s_nop 3
	global_load_dword v0, v1, s[2:3] offset:12 sc1
	s_mov_b64 s[2:3], -1
	s_waitcnt vmcnt(0)
	v_cmp_gt_u32_e32 vcc, 64, v0
	s_cbranch_vccz .LBB0_1082
	v_readlane_b32 s2, v252, 43
	v_readlane_b32 s3, v252, 44
	s_sleep 1
	s_nop 3
	global_load_dword v0, v1, s[2:3] offset:12 sc1
	s_mov_b64 s[2:3], -1
	s_waitcnt vmcnt(0)
	v_cmp_gt_u32_e32 vcc, 64, v0
	s_cbranch_vccz .LBB0_1082
	v_readlane_b32 s2, v252, 43
	v_readlane_b32 s3, v252, 44
	s_sleep 1
	s_nop 3
	global_load_dword v0, v1, s[2:3] offset:12 sc1
	s_mov_b64 s[2:3], -1
	s_waitcnt vmcnt(0)
	v_cmp_gt_u32_e32 vcc, 64, v0
	s_cbranch_vccz .LBB0_1082
	v_readlane_b32 s2, v252, 43
	v_readlane_b32 s3, v252, 44
	s_sleep 1
	s_nop 3
	global_load_dword v0, v1, s[2:3] offset:12 sc1
	s_mov_b64 s[2:3], -1
	s_waitcnt vmcnt(0)
	v_cmp_gt_u32_e32 vcc, 64, v0
	s_cbranch_vccz .LBB0_1082
	v_readlane_b32 s2, v252, 43
	v_readlane_b32 s3, v252, 44
	s_sleep 1
	s_nop 3
	global_load_dword v0, v1, s[2:3] offset:12 sc1
	s_mov_b64 s[2:3], -1
	s_waitcnt vmcnt(0)
	v_cmp_gt_u32_e32 vcc, 64, v0
	s_cbranch_vccz .LBB0_1082
	v_readlane_b32 s2, v252, 43
	v_readlane_b32 s3, v252, 44
	s_sleep 1
	s_nop 3
	global_load_dword v0, v1, s[2:3] offset:12 sc1
	s_mov_b64 s[2:3], -1
	s_waitcnt vmcnt(0)
	v_cmp_gt_u32_e32 vcc, 64, v0
	s_cbranch_vccz .LBB0_1082
	s_sleep 1
	s_add_i32 s4, s4, -8
	s_mov_b64 s[2:3], 0
	s_branch .LBB0_1082
.LBB0_1093:
	s_waitcnt vmcnt(0)
.LBB0_1094:
	s_or_b64 exec, exec, s[0:1]
	v_readlane_b32 s0, v252, 40
	v_mov_b32_e32 v2, v248
	s_mov_b32 s2, s0
	s_barrier
	s_cmpk_gt_i32 s2, 0x7ff
	s_cbranch_scc1 .LBB0_1106
	v_readlane_b32 s4, v251, 2
	v_ashrrev_i32_e32 v3, 31, v2
	v_readlane_b32 s5, v251, 3
	v_ashrrev_i32_e32 v9, 2, v2
	s_movk_i32 s0, 0x80
	v_lshl_add_u64 v[4:5], v[2:3], 2, s[4:5]
	v_readlane_b32 s4, v251, 6
	v_readlane_b32 s5, v251, 7
	v_and_b32_e32 v8, 0x7f, v2
	v_and_b32_e32 v10, 0xffffffe0, v9
	v_lshl_add_u64 v[6:7], v[2:3], 1, s[4:5]
	v_or_b32_e32 v3, 31, v9
	v_lshrrev_b32_e32 v9, 5, v9
	v_cmp_gt_i32_e64 s[0:1], s0, v2
	v_lshl_add_u32 v0, v2, 2, 0
	v_add_u32_e32 v10, -1, v10
	v_lshl_or_b32 v11, v9, 12, v8
	v_lshl_add_u32 v12, v9, 7, 0
	s_branch .LBB0_1097

; DI int ltid() { int t = threadIdx.x; asm volatile("" : "+v"(t)); return t; }
; DI int fetch_item(unsigned* ctr0, int* slot) {
;   __syncthreads();
;   unsigned long long ca = (unsigned long long)ctr0; asm volatile("" : "+s"(ca));
;   unsigned* ctr = (unsigned*)ca;
;   if (ltid() == 0) *slot = (int)atomicAdd(ctr, 1u);
;   __syncthreads();
;   return *slot;
; __global__ void __launch_bounds__(NTHR) fwd_megakernel(Params p) {
;     ...
;       for (;;) {
;         const int it = fetch_item(ctr + l * 4 + 1, slot);
;         if (it >= 256) break;
.LBB0_1157:
	s_mov_b64 s[4:5], s[6:7]
	v_mov_b32_e32 v0, v248
	s_barrier
	s_nop 0
	v_cmp_eq_u32_e32 vcc, 0, v0
	s_and_saveexec_b64 s[2:3], vcc
	s_cbranch_execz .LBB0_1159
	v_mov_b64_e32 v[2:3], s[4:5]
	s_cmp_eq_u32 s100, 0
	s_cbranch_scc1 .Lfq1_static
	v_mov_b32_e32 v0, 0x100
	s_branch .Lfq1_join
